# ssd_pass1 + ssd_pass3: per-unit conv weights staged once in LDS, head loops read them with ds_read_b128 instead of serialized global round trips
# baseline (speedup 1.0000x reference)
.LBB0_931:
	s_or_b64 exec, exec, s[4:5]
	v_lshlrev_b32_e32 v1, 3, v40
	v_and_b32_e32 v19, 0x78, v1
	v_lshl_or_b32 v2, s14, 7, v19
	v_or_b32_e32 v20, 0x400, v2
	v_lshlrev_b32_e32 v10, 2, v20
	global_load_dwordx4 v[2:5], v10, s[22:23] offset:16
	global_load_dwordx4 v[6:9], v10, s[22:23]
	v_ashrrev_i32_e32 v18, 4, v40
	v_mov_b32_e32 v11, v0
	v_lshl_add_u64 v[10:11], s[20:21], 0, v[10:11]
	s_mov_b64 s[4:5], 0x1800
	v_mul_u32_u24_e32 v19, 0x110, v19
	v_lshlrev_b32_e32 v21, 1, v18
	s_add_u32 s40, s8, s10
	v_lshl_add_u64 v[12:13], v[10:11], 0, s[4:5]
	s_mov_b64 s[4:5], 0x3000
	v_add3_u32 v38, v19, v21, 0
	s_addc_u32 s41, s9, 0
	v_ashrrev_i32_e32 v19, 31, v18
	v_lshl_add_u64 v[14:15], v[10:11], 0, s[4:5]
	s_mov_b64 s[4:5], 0x4800
	v_add_u32_e32 v39, s10, v18
	v_lshl_add_u64 v[18:19], s[40:41], 0, v[18:19]
	v_lshlrev_b32_e32 v20, 1, v20
	v_mov_b32_e32 v21, v0
	v_lshl_add_u64 v[16:17], v[10:11], 0, s[4:5]
	v_mad_u64_u32 v[20:21], s[4:5], v18, s84, v[20:21]
	v_mad_i32_i24 v21, v19, s84, v21
	s_mov_b32 s7, s9
	v_lshl_add_u64 v[18:19], s[2:3], 0, v[20:21]
	s_mov_b64 s[4:5], 0
	global_load_dwordx4 v[50:53], v[10:11], off
	global_load_dwordx4 v[54:57], v[10:11], off offset:16
	global_load_dwordx4 v[58:61], v[12:13], off
	global_load_dwordx4 v[62:65], v[12:13], off offset:16
	global_load_dwordx4 v[66:69], v[14:15], off
	global_load_dwordx4 v[70:73], v[14:15], off offset:16
	global_load_dwordx4 v[74:77], v[16:17], off
	global_load_dwordx4 v[78:81], v[16:17], off offset:16
	v_lshrrev_b32_e32 v222, 6, v178
	v_and_b32_e32 v223, 7, v178
	v_bfe_u32 v224, v178, 3, 3
	v_lshlrev_b32_e32 v225, 6, v222
	v_lshl_add_u32 v225, v223, 3, v225
	v_mov_b32_e32 v226, s14
	v_lshl_add_u32 v225, v226, 9, v225
	v_lshrrev_b32_e32 v226, 1, v224
	v_mul_u32_u24_e32 v226, 0x600, v226
	v_add_u32_e32 v226, v226, v225
	v_and_b32_e32 v227, 1, v224
	v_lshlrev_b32_e32 v233, 2, v227
	v_add_lshl_u32 v226, v226, v233, 2
	global_load_dwordx4 v[228:231], v226, s[20:21]
	v_add_lshl_u32 v233, v225, v233, 2
	global_load_dwordx4 v[246:249], v233, s[22:23]
	v_mul_u32_u24_e32 v232, 0x500, v222
	v_lshl_add_u32 v232, v223, 4, v232
	v_add_u32_e32 v232, 0x24000, v232
	v_lshl_add_u32 v233, v227, 7, v232
	v_lshl_add_u32 v232, v224, 7, v232
	s_branch .LBB0_933

.LBB0_941:
	v_ashrrev_i32_e32 v36, 3, v40
	v_ashrrev_i32_e32 v37, 31, v36
	v_lshl_add_u64 v[20:21], s[6:7], 0, v[36:37]
	v_mov_b64_e32 v[2:3], s[28:29]
	v_mul_lo_u32 v21, v21, s84
	v_mad_u64_u32 v[2:3], s[4:5], v20, s84, v[2:3]
	v_and_b32_e32 v41, 56, v1
	v_add_u32_e32 v3, v21, v3
	s_lshl_b32 s42, s14, 10
	s_mov_b32 s43, s81
	v_lshl_add_u64 v[2:3], v[2:3], 0, s[42:43]
	v_lshlrev_b32_e32 v22, 1, v41
	v_mov_b32_e32 v23, v0
	v_mov_b32_e32 v6, v0
	v_mov_b32_e32 v7, v0
	v_add_u32_e32 v32, s10, v36
	v_lshl_add_u64 v[2:3], v[2:3], 0, v[22:23]
	s_mov_b64 s[4:5], 0x1800
	v_mov_b32_e32 v4, v0
	v_mov_b32_e32 v5, v0
	v_mov_b64_e32 v[10:11], v[6:7]
	v_lshl_add_u64 v[24:25], v[2:3], 0, s[4:5]
	v_cmp_lt_i32_e64 s[4:5], 2, v32
	v_mov_b64_e32 v[8:9], v[4:5]
	s_waitcnt vmcnt(0)
	ds_write_b128 v232, v[228:231]
	ds_write_b128 v233, v[246:249] offset:1024
	v_mov_b32_e32 v222, 0x24000
	v_lshl_add_u32 v222, v223, 4, v222
	s_waitcnt lgkmcnt(0)
	s_barrier
	s_and_saveexec_b64 s[6:7], s[4:5]
	s_cbranch_execz .LBB0_943
	v_add_co_u32_e32 v2, vcc, 0xffffa000, v24
	s_nop 1
	v_addc_co_u32_e32 v3, vcc, -1, v25, vcc
	global_load_dwordx4 v[8:11], v[2:3], off offset:-3072

.LBB0_960:
	v_lshl_add_u64 v[2:3], v[76:77], 0, s[38:39]
	v_lshl_add_u64 v[40:41], v[82:83], 0, s[38:39]
	v_mov_b32_e32 v1, s33
	ds_read_b32 v1, v1 offset:4604
	ds_read_b128 v[36:39], v222 offset:1152
	s_nop 0
	ds_read_b128 v[40:43], v222 offset:1024
	s_nop 0
	ds_read_b128 v[44:47], v222 offset:128
	ds_read_b128 v[48:51], v222
	s_waitcnt vmcnt(0)
	v_lshlrev_b32_e32 v52, 16, v8
	s_mov_b64 s[40:41], 0x1800
	v_and_b32_e32 v53, 0xffff0000, v8
	v_lshl_add_u64 v[56:57], v[2:3], 0, s[40:41]
	v_lshlrev_b32_e32 v54, 16, v9
	v_and_b32_e32 v55, 0xffff0000, v9
	v_lshlrev_b32_e32 v58, 16, v10
	v_and_b32_e32 v59, 0xffff0000, v10
	s_mov_b64 s[40:41], 0x3000
	v_lshl_add_u64 v[64:65], v[2:3], 0, s[40:41]
	s_mov_b64 s[40:41], 0x4800
	v_lshlrev_b32_e32 v60, 16, v11
	v_lshl_add_u64 v[72:73], v[2:3], 0, s[40:41]
	v_and_b32_e32 v61, 0xffff0000, v11
	s_movk_i32 s40, 0x3000
	v_lshlrev_b32_e32 v62, 16, v5
	v_and_b32_e32 v63, 0xffff0000, v5
	v_lshlrev_b32_e32 v66, 16, v6
	v_and_b32_e32 v67, 0xffff0000, v6
	v_lshlrev_b32_e32 v68, 16, v7
	v_and_b32_e32 v69, 0xffff0000, v7
	v_lshlrev_b32_e32 v70, 16, v13
	v_and_b32_e32 v71, 0xffff0000, v13
	v_lshlrev_b32_e32 v74, 16, v14
	v_and_b32_e32 v75, 0xffff0000, v14
	v_lshlrev_b32_e32 v84, 16, v15
	v_and_b32_e32 v85, 0xffff0000, v15
	v_lshlrev_b32_e32 v101, 16, v17
	v_and_b32_e32 v102, 0xffff0000, v17
	v_lshlrev_b32_e32 v103, 16, v18
	v_and_b32_e32 v104, 0xffff0000, v18
	v_lshlrev_b32_e32 v105, 16, v19
	v_and_b32_e32 v106, 0xffff0000, v19
	s_cmpk_eq_i32 s38, 0x700
	s_waitcnt lgkmcnt(0)
	v_fma_f32 v96, v44, v58, v36
	s_nop 0
	v_fma_f32 v100, v48, v52, v40
	v_add_co_u32_e32 v52, vcc, s69, v2
	v_fma_f32 v99, v49, v53, v41
	s_nop 0
	v_addc_co_u32_e32 v53, vcc, 0, v3, vcc
	v_fma_f32 v95, v45, v59, v37
	v_fma_f32 v98, v50, v54, v42
	v_fma_f32 v97, v51, v55, v43
	ds_read_b128 v[52:55], v222 offset:256
	s_nop 0
	ds_read_b128 v[56:59], v222 offset:384
	v_fma_f32 v94, v46, v60, v38
	v_lshlrev_b32_e32 v60, 16, v4
	v_fma_f32 v93, v47, v61, v39
	v_and_b32_e32 v61, 0xffff0000, v4
	s_waitcnt lgkmcnt(0)
	v_fmac_f32_e32 v100, v52, v60
	v_add_co_u32_e32 v60, vcc, s40, v2
	v_fmac_f32_e32 v99, v53, v61
	s_nop 0
	v_addc_co_u32_e32 v61, vcc, 0, v3, vcc
	s_nop 0
	v_fmac_f32_e32 v96, v56, v66
	v_fmac_f32_e32 v95, v57, v67
	v_fmac_f32_e32 v98, v54, v62
	v_fmac_f32_e32 v97, v55, v63
	ds_read_b128 v[60:63], v222 offset:512
	s_nop 0
	ds_read_b128 v[64:67], v222 offset:640
	s_movk_i32 s40, 0x4000
	v_add_co_u32_e32 v2, vcc, s40, v2
	v_fmac_f32_e32 v94, v58, v68
	v_fmac_f32_e32 v93, v59, v69
	v_lshlrev_b32_e32 v68, 16, v12
	v_and_b32_e32 v69, 0xffff0000, v12
	v_addc_co_u32_e32 v3, vcc, 0, v3, vcc
	s_waitcnt lgkmcnt(0)
	v_fmac_f32_e32 v100, v60, v68
	s_nop 0
	v_fmac_f32_e32 v96, v64, v74
	v_fmac_f32_e32 v99, v61, v69
	v_fmac_f32_e32 v95, v65, v75
	v_fmac_f32_e32 v98, v62, v70
	v_fmac_f32_e32 v97, v63, v71
	ds_read_b128 v[68:71], v222 offset:768
	s_nop 0
	ds_read_b128 v[72:75], v222 offset:896
	v_add_u32_e32 v222, 0x500, v222
	v_fmac_f32_e32 v94, v66, v84
	v_lshlrev_b32_e32 v84, 16, v16
	v_fmac_f32_e32 v93, v67, v85
	v_and_b32_e32 v85, 0xffff0000, v16
	s_waitcnt lgkmcnt(0)
	v_fmac_f32_e32 v100, v68, v84
	v_add_u32_e32 v84, s33, v87
	v_fmac_f32_e32 v99, v69, v85
	ds_read2st64_b32 v[2:3], v84 offset1:1
	ds_read2st64_b32 v[84:85], v84 offset0:16 offset1:17
	v_fmac_f32_e32 v98, v70, v101
	v_fmac_f32_e32 v97, v71, v102
	s_nop 0
	v_fmac_f32_e32 v96, v72, v103
	v_fmac_f32_e32 v95, v73, v104
	s_waitcnt lgkmcnt(0)
	v_sub_f32_e32 v84, v1, v84
	v_mul_f32_e32 v84, 0x3fb8aa3b, v84
	v_exp_f32_e32 v84, v84
	v_fmac_f32_e32 v94, v74, v105
	v_fmac_f32_e32 v93, v75, v106
	v_sub_f32_e32 v1, v1, v85
	v_mul_f32_e32 v2, v2, v84
	v_mul_f32_e32 v84, 0xbfb8aa3b, v100
	v_exp_f32_e32 v84, v84
	v_mul_f32_e32 v1, 0x3fb8aa3b, v1
	v_exp_f32_e32 v1, v1
	v_add_f32_e32 v84, 1.0, v84
	v_rcp_f32_e32 v84, v84
	v_mul_f32_e32 v1, v3, v1
	v_mul_f32_e32 v84, v100, v84
	v_mul_f32_e32 v84, v2, v84
	v_cvt_pk_bf16_f32 v84, v84, s0
	ds_write_b16 v88, v84 offset:34816
	v_mul_f32_e32 v84, 0xbfb8aa3b, v99
	v_exp_f32_e32 v84, v84
	s_nop 0
	v_add_f32_e32 v84, 1.0, v84
	v_rcp_f32_e32 v84, v84
	s_nop 0
	v_mul_f32_e32 v84, v99, v84
	v_mul_f32_e32 v84, v2, v84
	v_cvt_pk_bf16_f32 v84, v84, s0
	ds_write_b16 v88, v84 offset:35088
	v_mul_f32_e32 v84, 0xbfb8aa3b, v98
	v_exp_f32_e32 v84, v84
	s_nop 0
	v_add_f32_e32 v84, 1.0, v84
	v_rcp_f32_e32 v84, v84
	s_nop 0
	v_mul_f32_e32 v84, v98, v84
	v_mul_f32_e32 v84, v2, v84
	v_cvt_pk_bf16_f32 v84, v84, s0
	ds_write_b16 v88, v84 offset:35360
	v_mul_f32_e32 v84, 0xbfb8aa3b, v97
	v_exp_f32_e32 v84, v84
	v_and_b32_e32 v98, 0xffff0000, v23
	v_fmac_f32_e32 v39, v47, v98
	v_lshlrev_b32_e32 v47, 16, v26
	v_add_f32_e32 v84, 1.0, v84
	v_rcp_f32_e32 v84, v84
	s_nop 0
	v_mul_f32_e32 v84, v97, v84
	v_mul_f32_e32 v84, v2, v84
	v_cvt_pk_bf16_f32 v84, v84, s0
	ds_write_b16 v88, v84 offset:35632
	v_mul_f32_e32 v84, 0xbfb8aa3b, v96
	v_exp_f32_e32 v84, v84
	v_lshlrev_b32_e32 v97, 16, v23
	v_fma_f32 v38, v46, v97, v38
	v_and_b32_e32 v46, 0xffff0000, v25
	v_add_f32_e32 v84, 1.0, v84
	v_rcp_f32_e32 v84, v84
	s_nop 0
	v_mul_f32_e32 v84, v96, v84
	v_mul_f32_e32 v84, v2, v84
	v_cvt_pk_bf16_f32 v84, v84, s0
	ds_write_b16 v88, v84 offset:35904
	v_mul_f32_e32 v84, 0xbfb8aa3b, v95
	v_exp_f32_e32 v84, v84
	v_and_b32_e32 v96, 0xffff0000, v22
	v_fma_f32 v37, v45, v96, v37
	v_lshlrev_b32_e32 v45, 16, v25
	v_add_f32_e32 v84, 1.0, v84
	v_rcp_f32_e32 v84, v84
	s_nop 0
	v_mul_f32_e32 v84, v95, v84
	v_mul_f32_e32 v84, v2, v84
	v_cvt_pk_bf16_f32 v84, v84, s0
	ds_write_b16 v88, v84 offset:36176
	v_mul_f32_e32 v84, 0xbfb8aa3b, v94
	v_exp_f32_e32 v84, v84
	v_lshlrev_b32_e32 v95, 16, v22
	v_fma_f32 v36, v44, v95, v36
	v_and_b32_e32 v44, 0xffff0000, v24
	v_add_f32_e32 v84, 1.0, v84
	v_rcp_f32_e32 v84, v84
	v_fmac_f32_e32 v36, v56, v47
	v_lshlrev_b32_e32 v47, 16, v30
	v_fmac_f32_e32 v36, v64, v47
	v_mul_f32_e32 v84, v94, v84
	v_mul_f32_e32 v84, v2, v84
	v_cvt_pk_bf16_f32 v84, v84, s0
	ds_write_b16 v88, v84 offset:36448
	v_mul_f32_e32 v84, 0xbfb8aa3b, v93
	v_exp_f32_e32 v84, v84
	v_and_b32_e32 v94, 0xffff0000, v21
	v_fmac_f32_e32 v43, v51, v94
	v_fmac_f32_e32 v43, v55, v46
	v_add_f32_e32 v84, 1.0, v84
	v_rcp_f32_e32 v84, v84
	v_and_b32_e32 v46, 0xffff0000, v29
	v_fmac_f32_e32 v43, v63, v46
	v_and_b32_e32 v46, 0xffff0000, v33
	v_mul_f32_e32 v84, v93, v84
	v_mul_f32_e32 v2, v2, v84
	v_cvt_pk_bf16_f32 v2, v2, s0
	ds_write_b16 v88, v2 offset:36720
	v_lshlrev_b32_e32 v2, 16, v20
	v_and_b32_e32 v84, 0xffff0000, v20
	v_lshlrev_b32_e32 v93, 16, v21
	v_fma_f32 v2, v48, v2, v40
	v_fma_f32 v40, v49, v84, v41
	v_fma_f32 v41, v50, v93, v42
	v_lshlrev_b32_e32 v42, 16, v24
	v_fmac_f32_e32 v2, v52, v42
	v_lshlrev_b32_e32 v42, 16, v28
	v_fmac_f32_e32 v2, v60, v42
	v_lshlrev_b32_e32 v42, 16, v32
	v_fmac_f32_e32 v2, v68, v42
	v_mul_f32_e32 v3, 0xbfb8aa3b, v2
	v_exp_f32_e32 v3, v3
	v_fmac_f32_e32 v40, v53, v44
	v_and_b32_e32 v44, 0xffff0000, v28
	v_fmac_f32_e32 v40, v61, v44
	v_add_f32_e32 v3, 1.0, v3
	v_rcp_f32_e32 v3, v3
	v_and_b32_e32 v44, 0xffff0000, v32
	v_fmac_f32_e32 v40, v69, v44
	v_fmac_f32_e32 v41, v54, v45
	v_mul_f32_e32 v2, v2, v3
	v_mul_f32_e32 v2, v2, v1
	v_cvt_pk_bf16_f32 v2, v2, s0
	ds_write_b16 v88, v2 offset:34944
	v_mul_f32_e32 v2, 0xbfb8aa3b, v40
	v_exp_f32_e32 v2, v2
	v_lshlrev_b32_e32 v45, 16, v29
	v_fmac_f32_e32 v41, v62, v45
	v_lshlrev_b32_e32 v45, 16, v33
	v_add_f32_e32 v2, 1.0, v2
	v_rcp_f32_e32 v2, v2
	v_fmac_f32_e32 v41, v70, v45
	v_fmac_f32_e32 v43, v71, v46
	v_lshlrev_b32_e32 v47, 16, v34
	v_mul_f32_e32 v2, v40, v2
	v_mul_f32_e32 v2, v2, v1
	v_cvt_pk_bf16_f32 v2, v2, s0
	ds_write_b16 v88, v2 offset:35216
	v_mul_f32_e32 v2, 0xbfb8aa3b, v41
	v_exp_f32_e32 v2, v2
	v_fmac_f32_e32 v36, v72, v47
	v_and_b32_e32 v48, 0xffff0000, v26
	v_fmac_f32_e32 v37, v57, v48
	v_add_f32_e32 v2, 1.0, v2
	v_rcp_f32_e32 v2, v2
	v_and_b32_e32 v48, 0xffff0000, v30
	v_fmac_f32_e32 v37, v65, v48
	v_and_b32_e32 v48, 0xffff0000, v34
	v_mul_f32_e32 v2, v41, v2
	v_mul_f32_e32 v2, v2, v1
	v_cvt_pk_bf16_f32 v2, v2, s0
	ds_write_b16 v88, v2 offset:35488
	v_mul_f32_e32 v2, 0xbfb8aa3b, v43
	v_exp_f32_e32 v2, v2
	v_fmac_f32_e32 v37, v73, v48
	v_lshlrev_b32_e32 v49, 16, v27
	v_fmac_f32_e32 v38, v58, v49
	v_add_f32_e32 v2, 1.0, v2
	v_rcp_f32_e32 v2, v2
	v_lshlrev_b32_e32 v49, 16, v31
	v_fmac_f32_e32 v38, v66, v49
	v_lshlrev_b32_e32 v49, 16, v35
	v_mul_f32_e32 v2, v43, v2
	v_mul_f32_e32 v2, v2, v1
	v_cvt_pk_bf16_f32 v2, v2, s0
	ds_write_b16 v88, v2 offset:35760
	v_mul_f32_e32 v2, 0xbfb8aa3b, v36
	v_exp_f32_e32 v2, v2
	v_fmac_f32_e32 v38, v74, v49
	v_and_b32_e32 v50, 0xffff0000, v27
	v_fmac_f32_e32 v39, v59, v50
	v_add_f32_e32 v2, 1.0, v2
	v_rcp_f32_e32 v2, v2
	v_and_b32_e32 v50, 0xffff0000, v31
	v_fmac_f32_e32 v39, v67, v50
	v_and_b32_e32 v50, 0xffff0000, v35
	v_mul_f32_e32 v2, v36, v2
	v_mul_f32_e32 v2, v2, v1
	v_cvt_pk_bf16_f32 v2, v2, s0
	ds_write_b16 v88, v2 offset:36032
	v_mul_f32_e32 v2, 0xbfb8aa3b, v37
	v_exp_f32_e32 v2, v2
	v_fmac_f32_e32 v39, v75, v50
	v_add_f32_e32 v2, 1.0, v2
	v_rcp_f32_e32 v2, v2
	s_nop 0
	v_mul_f32_e32 v2, v37, v2
	v_mul_f32_e32 v2, v2, v1
	v_cvt_pk_bf16_f32 v2, v2, s0
	ds_write_b16 v88, v2 offset:36304
	v_mul_f32_e32 v2, 0xbfb8aa3b, v38
	v_exp_f32_e32 v2, v2
	s_nop 0
	v_add_f32_e32 v2, 1.0, v2
	v_rcp_f32_e32 v2, v2
	s_nop 0
	v_mul_f32_e32 v2, v38, v2
	v_mul_f32_e32 v2, v2, v1
	v_cvt_pk_bf16_f32 v2, v2, s0
	ds_write_b16 v88, v2 offset:36576
	v_mul_f32_e32 v2, 0xbfb8aa3b, v39
	v_exp_f32_e32 v2, v2
	s_nop 0
	v_add_f32_e32 v2, 1.0, v2
	v_rcp_f32_e32 v2, v2
	s_nop 0
	v_mul_f32_e32 v2, v39, v2
	v_mul_f32_e32 v1, v2, v1
	v_cvt_pk_bf16_f32 v1, v1, s0
	ds_write_b16 v88, v1 offset:36848
	s_waitcnt lgkmcnt(0)
	s_barrier
	s_cbranch_scc1 .LBB0_959
	v_mov_b32_e32 v6, v0
	v_mov_b32_e32 v7, v0
	v_mov_b32_e32 v4, v0
	v_mov_b32_e32 v5, v0
	v_mov_b64_e32 v[10:11], v[6:7]
	v_lshl_add_u64 v[36:37], s[2:3], 0, v[80:81]
	v_mov_b64_e32 v[8:9], v[4:5]
	s_and_saveexec_b64 s[40:41], s[4:5]
	s_cbranch_execz .LBB0_963
	v_add_co_u32_e32 v2, vcc, 0x31fa000, v36
	s_nop 1
	v_addc_co_u32_e32 v3, vcc, 0, v37, vcc
	global_load_dwordx4 v[8:11], v[2:3], off offset:3200

.LBB0_1099:
	s_and_b32 s76, s68, 1
	v_mov_b32_e32 v86, v178
	v_mov_b32_e32 v1, v178
	s_lshl_b32 s13, s76, 3
	v_ashrrev_i32_e32 v6, 6, v1
	v_add_u32_e32 v2, s13, v6
	s_ashr_i32 s4, s68, 7
	v_ashrrev_i32_e32 v3, 31, v2
	s_bfe_u32 s20, s68, 0x60001
	s_ashr_i32 s5, s4, 31
	v_mov_b32_e32 v1, v178
	v_lshlrev_b64 v[2:3], 2, v[2:3]
	s_lshl_b64 s[6:7], s[4:5], 13
	s_lshl_b32 s12, s20, 7
	v_lshl_add_u64 v[4:5], s[94:95], 0, v[2:3]
	v_writelane_b32 v255, s68, 41
	s_or_b32 s86, s6, s12
	v_and_b32_e32 v7, 63, v1
	global_load_dword v1, v[4:5], off
	v_lshl_add_u64 v[4:5], s[92:93], 0, v[2:3]
	global_load_dword v8, v[4:5], off
	v_or_b32_e32 v4, s86, v7
	v_mov_b32_e32 v5, s7
	v_readlane_b32 s8, v255, 35
	v_lshlrev_b64 v[4:5], 6, v[4:5]
	v_readlane_b32 s9, v255, 36
	v_add_u32_e32 v9, -4, v234
	v_add_u32_e32 v10, -8, v234
	v_lshl_add_u64 v[4:5], s[8:9], 0, v[4:5]
	v_lshl_add_u64 v[2:3], v[4:5], 0, v[2:3]
	global_load_dword v4, v[2:3], off
	v_add_co_u32_e32 v2, vcc, s69, v2
	v_add_u32_e32 v5, -2, v234
	s_nop 0
	v_addc_co_u32_e32 v3, vcc, 0, v3, vcc
	global_load_dword v2, v[2:3], off
	v_add_u32_e32 v3, -1, v234
	v_cmp_lt_i32_e32 vcc, v3, v242
	v_add_u32_e32 v11, -16, v234
	v_subrev_u32_e32 v12, 32, v234
	v_cndmask_b32_e32 v3, v3, v234, vcc
	v_cmp_lt_i32_e32 vcc, v5, v242
	v_lshlrev_b32_e32 v3, 2, v3
	v_lshl_or_b32 v13, v234, 2, v244
	v_cndmask_b32_e32 v5, v5, v234, vcc
	v_cmp_lt_i32_e32 vcc, v9, v242
	v_lshlrev_b32_e32 v5, 2, v5
	v_readlane_b32 s8, v255, 20
	v_cndmask_b32_e32 v9, v9, v234, vcc
	v_cmp_lt_i32_e32 vcc, v10, v242
	v_lshlrev_b32_e32 v9, 2, v9
	s_mov_b32 s5, 0
	v_cndmask_b32_e32 v10, v10, v234, vcc
	v_lshlrev_b32_e32 v10, 2, v10
	s_mov_b32 s87, s7
	s_waitcnt vmcnt(3)
	v_mul_f32_e32 v1, 0x3fb8aa3b, v1
	v_exp_f32_e32 v1, v1
	s_waitcnt vmcnt(1)
	v_add_f32_e32 v4, v8, v4
	v_max_f32_e32 v14, 0, v4
	v_mul_f32_e64 v4, |v4|, s72
	v_exp_f32_e32 v4, v4
	s_waitcnt vmcnt(0)
	v_add_f32_e32 v2, v8, v2
	v_max_f32_e32 v8, 0, v2
	v_mul_f32_e64 v2, |v2|, s72
	v_exp_f32_e32 v2, v2
	v_add_f32_e32 v4, 1.0, v4
	v_cmp_gt_f32_e32 vcc, s71, v4
	v_add_f32_e32 v2, 1.0, v2
	s_nop 0
	v_cndmask_b32_e64 v15, 0, 32, vcc
	v_ldexp_f32 v4, v4, v15
	v_cndmask_b32_e32 v15, 0, v243, vcc
	v_cmp_gt_f32_e32 vcc, s71, v2
	v_log_f32_e32 v4, v4
	s_nop 0
	v_cndmask_b32_e64 v16, 0, 32, vcc
	v_ldexp_f32 v2, v2, v16
	v_log_f32_e32 v2, v2
	v_mul_f32_e32 v17, 0x3f317217, v4
	v_fma_f32 v17, v4, s73, -v17
	v_fmac_f32_e32 v17, 0x3377d1cf, v4
	v_mul_f32_e32 v18, 0x3f317217, v2
	v_fma_f32 v18, v2, s73, -v18
	v_cndmask_b32_e32 v16, 0, v243, vcc
	v_fmac_f32_e32 v17, 0x3f317217, v4
	v_fmac_f32_e32 v18, 0x3377d1cf, v2
	v_cmp_lt_f32_e64 vcc, |v4|, s74
	v_fmac_f32_e32 v18, 0x3f317217, v2
	s_nop 0
	v_cndmask_b32_e32 v4, v4, v17, vcc
	v_cmp_lt_f32_e64 vcc, |v2|, s74
	v_sub_f32_e32 v4, v4, v15
	v_add_f32_e32 v4, v14, v4
	v_cndmask_b32_e32 v2, v2, v18, vcc
	v_sub_f32_e32 v2, v2, v16
	v_add_f32_e32 v2, v8, v2
	v_mul_f32_e64 v8, v4, -v1
	v_mul_f32_e64 v14, v2, -v1
	ds_bpermute_b32 v15, v3, v8
	ds_bpermute_b32 v3, v3, v14
	v_cmp_lt_i32_e32 vcc, v11, v242
	s_waitcnt lgkmcnt(1)
	v_fma_f32 v15, v4, -v1, v15
	v_cndmask_b32_e32 v11, v11, v234, vcc
	v_cmp_eq_u32_e32 vcc, 0, v7
	s_waitcnt lgkmcnt(0)
	v_fma_f32 v1, v2, -v1, v3
	v_lshlrev_b32_e32 v11, 2, v11
	v_cndmask_b32_e32 v3, v15, v8, vcc
	ds_bpermute_b32 v8, v5, v3
	v_cndmask_b32_e32 v1, v1, v14, vcc
	v_cmp_lt_i32_e32 vcc, v12, v242
	ds_bpermute_b32 v5, v5, v1
	s_waitcnt lgkmcnt(1)
	v_add_f32_e32 v8, v3, v8
	v_cndmask_b32_e32 v12, v12, v234, vcc
	v_cmp_gt_u32_e32 vcc, 2, v7
	s_waitcnt lgkmcnt(0)
	v_add_f32_e32 v5, v1, v5
	v_lshlrev_b32_e32 v12, 2, v12
	v_cndmask_b32_e32 v3, v8, v3, vcc
	ds_bpermute_b32 v8, v9, v3
	v_cndmask_b32_e32 v5, v5, v1, vcc
	ds_bpermute_b32 v9, v9, v5
	v_cmp_gt_u32_e32 vcc, 4, v7
	v_lshlrev_b32_e32 v1, 3, v86
	s_waitcnt lgkmcnt(1)
	v_add_f32_e32 v8, v3, v8
	v_cndmask_b32_e32 v3, v8, v3, vcc
	ds_bpermute_b32 v8, v10, v3
	s_waitcnt lgkmcnt(1)
	v_add_f32_e32 v9, v5, v9
	v_cndmask_b32_e32 v5, v9, v5, vcc
	ds_bpermute_b32 v9, v10, v5
	v_cmp_gt_u32_e32 vcc, 8, v7
	s_waitcnt lgkmcnt(1)
	v_add_f32_e32 v8, v3, v8
	v_lshlrev_b32_e32 v10, 2, v7
	v_cndmask_b32_e32 v3, v8, v3, vcc
	ds_bpermute_b32 v8, v11, v3
	s_waitcnt lgkmcnt(1)
	v_add_f32_e32 v9, v5, v9
	v_cndmask_b32_e32 v5, v9, v5, vcc
	ds_bpermute_b32 v9, v11, v5
	v_cmp_gt_u32_e32 vcc, 16, v7
	s_waitcnt lgkmcnt(1)
	v_add_f32_e32 v8, v3, v8
	v_lshl_or_b32 v6, v6, 9, v10
	v_cndmask_b32_e32 v3, v8, v3, vcc
	ds_bpermute_b32 v8, v12, v3
	s_waitcnt lgkmcnt(1)
	v_add_f32_e32 v9, v5, v9
	v_cndmask_b32_e32 v5, v9, v5, vcc
	ds_bpermute_b32 v9, v12, v5
	v_cmp_gt_u32_e32 vcc, 32, v7
	s_waitcnt lgkmcnt(1)
	v_add_f32_e32 v8, v3, v8
	v_and_b32_e32 v14, 0x78, v1
	v_cndmask_b32_e32 v3, v8, v3, vcc
	ds_bpermute_b32 v7, v13, v3
	v_or_b32_e32 v12, 0x100, v6
	s_waitcnt lgkmcnt(1)
	v_add_f32_e32 v9, v5, v9
	v_lshl_or_b32 v10, s76, 7, v14
	v_add_u32_e32 v11, s8, v6
	v_add_u32_e32 v15, s8, v12
	v_cndmask_b32_e32 v5, v9, v5, vcc
	v_add_u32_e32 v6, s85, v6
	v_add_u32_e32 v8, s85, v12
	ds_write_b32 v11, v4
	ds_write_b32 v15, v2
	ds_write_b32 v6, v3
	s_waitcnt lgkmcnt(3)
	v_add_f32_e32 v2, v5, v7
	v_or_b32_e32 v15, 0x400, v10
	ds_write_b32 v8, v2
	v_lshrrev_b32_e32 v222, 6, v178
	v_and_b32_e32 v223, 7, v178
	v_bfe_u32 v224, v178, 3, 3
	v_lshlrev_b32_e32 v225, 6, v222
	v_lshl_add_u32 v225, v223, 3, v225
	v_mov_b32_e32 v226, s76
	v_lshl_add_u32 v225, v226, 9, v225
	v_lshrrev_b32_e32 v226, 1, v224
	v_mul_u32_u24_e32 v226, 0x600, v226
	v_add_u32_e32 v226, v226, v225
	v_and_b32_e32 v227, 1, v224
	v_lshlrev_b32_e32 v233, 2, v227
	v_add_lshl_u32 v226, v226, v233, 2
	global_load_dwordx4 v[228:231], v226, s[88:89]
	v_add_lshl_u32 v233, v225, v233, 2
	global_load_dwordx4 v[246:249], v233, s[90:91]
	v_mul_u32_u24_e32 v232, 0x500, v222
	v_lshl_add_u32 v232, v223, 4, v232
	v_add_u32_e32 v232, 0x24000, v232
	v_lshl_add_u32 v233, v227, 7, v232
	v_lshl_add_u32 v232, v224, 7, v232
	s_branch .LBB0_1101

.LBB0_1107:
	v_ashrrev_i32_e32 v87, 6, v86
	v_and_b32_e32 v88, 15, v86
	v_bfe_u32 v151, v86, 4, 2
	v_lshl_or_b32 v148, v87, 4, v88
	v_lshl_add_u32 v150, v151, 4, 0
	s_movk_i32 s5, 0x110
	v_mad_u64_u32 v[2:3], s[8:9], v148, s5, v[150:151]
	s_waitcnt vmcnt(0)
	ds_write_b128 v232, v[228:231]
	ds_write_b128 v233, v[246:249] offset:1024
	v_mov_b32_e32 v222, 0x24000
	v_lshl_add_u32 v222, v223, 4, v222
	s_waitcnt lgkmcnt(0)
	s_barrier
	ds_read_b128 v[4:7], v2
	ds_read_b128 v[8:11], v2 offset:64
	ds_read_b128 v[12:15], v2 offset:128
	ds_read_b128 v[16:19], v2 offset:192
	v_mad_u32_u24 v2, v88, s5, v150
	ds_read_b128 v[20:23], v2 offset:34816
	ds_read_b128 v[24:27], v2 offset:34880
	s_waitcnt lgkmcnt(1)
	v_mfma_f32_16x16x32_bf16 v[20:23], v[20:23], v[4:7], 0
	ds_read_b128 v[28:31], v2 offset:39232
	v_ashrrev_i32_e32 v152, 3, v86
	v_ashrrev_i32_e32 v153, 31, v152
	s_waitcnt lgkmcnt(1)
	v_mfma_f32_16x16x32_bf16 v[20:23], v[24:27], v[8:11], v[20:23]
	ds_read_b128 v[24:27], v2 offset:34944
	ds_read_b128 v[32:35], v2 offset:43584
	v_lshl_add_u64 v[68:69], s[86:87], 0, v[152:153]
	s_waitcnt lgkmcnt(1)
	v_mfma_f32_16x16x32_bf16 v[20:23], v[24:27], v[12:15], v[20:23]
	ds_read_b128 v[24:27], v2 offset:35008
	ds_read_b128 v[36:39], v2 offset:47936
	v_mul_lo_u32 v69, v69, s84
	s_waitcnt lgkmcnt(1)
	v_mfma_f32_16x16x32_bf16 v[20:23], v[24:27], v[16:19], v[20:23]
	ds_read_b128 v[24:27], v2 offset:39168
	ds_read_b128 v[40:43], v2 offset:52288
	v_and_b32_e32 v89, 56, v1
	s_waitcnt lgkmcnt(1)
	v_mfma_f32_16x16x32_bf16 v[24:27], v[24:27], v[4:7], 0
	ds_read_b128 v[44:47], v2 offset:56640
	v_lshlrev_b32_e32 v70, 1, v89
	v_mov_b32_e32 v71, v0
	v_mfma_f32_16x16x32_bf16 v[24:27], v[28:31], v[8:11], v[24:27]
	ds_read_b128 v[28:31], v2 offset:39296
	s_mov_b64 s[10:11], 0x1800
	v_add_u32_e32 v80, s12, v152
	s_waitcnt lgkmcnt(0)
	v_mfma_f32_16x16x32_bf16 v[24:27], v[28:31], v[12:15], v[24:27]
	ds_read_b128 v[28:31], v2 offset:39360
	ds_read_b128 v[48:51], v2 offset:60992
	v_cmp_lt_i32_e64 s[14:15], 2, v80
	s_waitcnt lgkmcnt(1)
	v_mfma_f32_16x16x32_bf16 v[24:27], v[28:31], v[16:19], v[24:27]
	ds_read_b128 v[28:31], v2 offset:43520
	ds_read_b128 v[52:55], v2 offset:65344
	s_waitcnt lgkmcnt(1)
	v_mfma_f32_16x16x32_bf16 v[28:31], v[28:31], v[4:7], 0
	v_mfma_f32_16x16x32_bf16 v[28:31], v[32:35], v[8:11], v[28:31]
	ds_read_b128 v[32:35], v2 offset:43648
	s_waitcnt lgkmcnt(0)
	v_mfma_f32_16x16x32_bf16 v[28:31], v[32:35], v[12:15], v[28:31]
	ds_read_b128 v[32:35], v2 offset:43712
	s_waitcnt lgkmcnt(0)
	v_mfma_f32_16x16x32_bf16 v[28:31], v[32:35], v[16:19], v[28:31]
	ds_read_b128 v[32:35], v2 offset:47872
	s_waitcnt lgkmcnt(0)
	v_mfma_f32_16x16x32_bf16 v[32:35], v[32:35], v[4:7], 0
	v_mfma_f32_16x16x32_bf16 v[32:35], v[36:39], v[8:11], v[32:35]
	ds_read_b128 v[36:39], v2 offset:48000
	s_waitcnt lgkmcnt(0)
	v_mfma_f32_16x16x32_bf16 v[32:35], v[36:39], v[12:15], v[32:35]
	ds_read_b128 v[36:39], v2 offset:48064
	s_waitcnt lgkmcnt(0)
	v_mfma_f32_16x16x32_bf16 v[32:35], v[36:39], v[16:19], v[32:35]
	ds_read_b128 v[36:39], v2 offset:52224
	s_waitcnt lgkmcnt(0)
	v_mfma_f32_16x16x32_bf16 v[36:39], v[36:39], v[4:7], 0
	v_mfma_f32_16x16x32_bf16 v[36:39], v[40:43], v[8:11], v[36:39]
	ds_read_b128 v[40:43], v2 offset:52352
	s_waitcnt lgkmcnt(0)
	v_mfma_f32_16x16x32_bf16 v[36:39], v[40:43], v[12:15], v[36:39]
	ds_read_b128 v[40:43], v2 offset:52416
	s_waitcnt lgkmcnt(0)
	v_mfma_f32_16x16x32_bf16 v[36:39], v[40:43], v[16:19], v[36:39]
	ds_read_b128 v[40:43], v2 offset:56576
	s_waitcnt lgkmcnt(0)
	v_mfma_f32_16x16x32_bf16 v[40:43], v[40:43], v[4:7], 0
	v_mfma_f32_16x16x32_bf16 v[40:43], v[44:47], v[8:11], v[40:43]
	ds_read_b128 v[44:47], v2 offset:56704
	s_waitcnt lgkmcnt(0)
	v_mfma_f32_16x16x32_bf16 v[40:43], v[44:47], v[12:15], v[40:43]
	ds_read_b128 v[44:47], v2 offset:56768
	s_waitcnt lgkmcnt(0)
	v_mfma_f32_16x16x32_bf16 v[40:43], v[44:47], v[16:19], v[40:43]
	ds_read_b128 v[44:47], v2 offset:60928
	s_waitcnt lgkmcnt(0)
	v_mfma_f32_16x16x32_bf16 v[44:47], v[44:47], v[4:7], 0
	v_mfma_f32_16x16x32_bf16 v[44:47], v[48:51], v[8:11], v[44:47]
	ds_read_b128 v[48:51], v2 offset:61056
	s_waitcnt lgkmcnt(0)
	v_mfma_f32_16x16x32_bf16 v[44:47], v[48:51], v[12:15], v[44:47]
	ds_read_b128 v[48:51], v2 offset:61120
	s_waitcnt lgkmcnt(0)
	v_mfma_f32_16x16x32_bf16 v[44:47], v[48:51], v[16:19], v[44:47]
	ds_read_b128 v[48:51], v2 offset:65280
	s_waitcnt lgkmcnt(0)
	v_mfma_f32_16x16x32_bf16 v[48:51], v[48:51], v[4:7], 0
	v_mfma_f32_16x16x32_bf16 v[48:51], v[52:55], v[8:11], v[48:51]
	ds_read_b128 v[52:55], v2 offset:65408
	s_waitcnt lgkmcnt(0)
	v_mfma_f32_16x16x32_bf16 v[48:51], v[52:55], v[12:15], v[48:51]
	ds_read_b128 v[52:55], v2 offset:65472
	v_mov_b64_e32 v[2:3], s[96:97]
	v_mad_u64_u32 v[2:3], s[8:9], v68, s84, v[2:3]
	s_waitcnt lgkmcnt(0)
	v_mfma_f32_16x16x32_bf16 v[48:51], v[52:55], v[16:19], v[48:51]
	v_add_u32_e32 v3, v69, v3
	s_lshl_b32 s8, s76, 10
	s_mov_b32 s9, s81
	v_lshl_add_u64 v[2:3], v[2:3], 0, s[8:9]
	v_mov_b32_e32 v54, v0
	v_mov_b32_e32 v55, v0
	v_lshl_add_u64 v[2:3], v[2:3], 0, v[70:71]
	v_mov_b32_e32 v52, v0
	v_mov_b32_e32 v53, v0
	v_mov_b64_e32 v[58:59], v[54:55]
	v_lshl_add_u64 v[72:73], v[2:3], 0, s[10:11]
	v_mov_b64_e32 v[56:57], v[52:53]
	s_mov_b64 s[10:11], exec
	v_writelane_b32 v255, s14, 42
	s_nop 1
	v_writelane_b32 v255, s15, 43
	s_and_b64 s[14:15], s[10:11], s[14:15]
	s_mov_b64 exec, s[14:15]
	s_cbranch_execz .LBB0_1109
	v_add_co_u32_e32 v2, vcc, 0xffffa000, v72
	s_nop 1
	v_addc_co_u32_e32 v3, vcc, -1, v73, vcc
	global_load_dwordx4 v[56:59], v[2:3], off offset:-3072

.LBB0_1126:
	v_lshl_add_u64 v[2:3], s[6:7], 0, v[158:159]
	s_mov_b64 s[10:11], 0x1800
	v_lshl_add_u64 v[104:105], v[2:3], 0, s[10:11]
	s_movk_i32 s10, 0x1000
	v_add_co_u32_e32 v100, vcc, s10, v2
	s_mov_b64 s[10:11], 0x3000
	s_nop 0
	v_addc_co_u32_e32 v101, vcc, 0, v3, vcc
	v_lshl_add_u64 v[112:113], v[2:3], 0, s[10:11]
	s_movk_i32 s10, 0x3000
	v_lshl_add_u64 v[88:89], s[8:9], 0, v[158:159]
	v_add_co_u32_e32 v108, vcc, s10, v2
	s_mov_b64 s[10:11], 0x4800
	ds_read_b128 v[84:87], v222 offset:1152
	s_nop 0
	ds_read_b128 v[88:91], v222 offset:1024
	s_nop 0
	ds_read_b128 v[96:99], v222
	ds_read_b128 v[92:95], v222 offset:128
	v_addc_co_u32_e32 v109, vcc, 0, v3, vcc
	v_lshl_add_u64 v[116:117], v[2:3], 0, s[10:11]
	s_movk_i32 s10, 0x4000
	ds_read_b128 v[100:103], v222 offset:256
	s_nop 0
	ds_read_b128 v[104:107], v222 offset:384
	v_add_co_u32_e32 v2, vcc, s10, v2
	ds_read_b128 v[108:111], v222 offset:512
	s_nop 0
	ds_read_b128 v[112:115], v222 offset:640
	v_addc_co_u32_e32 v3, vcc, 0, v3, vcc
	ds_read_b128 v[120:123], v222 offset:768
	s_nop 0
	ds_read_b128 v[116:119], v222 offset:896
	v_add_u32_e32 v222, 0x500, v222
	v_lshl_add_u64 v[124:125], s[2:3], 0, v[156:157]
	s_mov_b32 s10, 0x19200000
	v_add_co_u32_e32 v2, vcc, s10, v124
	s_mov_b32 s10, 0x19201000
	s_nop 0
	v_addc_co_u32_e32 v3, vcc, 0, v125, vcc
	v_add_co_u32_e32 v130, vcc, s10, v124
	s_mov_b32 s10, 0x19202000
	s_nop 0
	v_addc_co_u32_e32 v131, vcc, 0, v125, vcc
	v_add_co_u32_e32 v128, vcc, s10, v124
	s_waitcnt vmcnt(0)
	v_lshlrev_b32_e32 v126, 16, v56
	v_addc_co_u32_e32 v129, vcc, 0, v125, vcc
	s_mov_b32 s10, 0x19203000
	v_lshlrev_b32_e32 v134, 16, v58
	v_lshlrev_b32_e32 v140, 16, v52
	v_add_co_u32_e32 v136, vcc, s10, v124
	v_and_b32_e32 v127, 0xffff0000, v56
	v_lshlrev_b32_e32 v144, 16, v54
	v_lshlrev_b32_e32 v155, 16, v60
	v_addc_co_u32_e32 v137, vcc, 0, v125, vcc
	v_and_b32_e32 v135, 0xffff0000, v58
	v_and_b32_e32 v139, 0xffff0000, v59
	v_and_b32_e32 v141, 0xffff0000, v52
	v_lshlrev_b32_e32 v173, 16, v62
	v_lshlrev_b32_e32 v177, 16, v64
	v_and_b32_e32 v145, 0xffff0000, v54
	v_and_b32_e32 v170, 0xffff0000, v60
	v_and_b32_e32 v174, 0xffff0000, v62
	v_and_b32_e32 v186, 0xffff0000, v64
	v_and_b32_e32 v133, 0xffff0000, v57
	v_and_b32_e32 v143, 0xffff0000, v53
	v_lshlrev_b32_e32 v138, 16, v59
	v_and_b32_e32 v172, 0xffff0000, v61
	s_bitcmp1_b32 s12, 0
	v_lshlrev_b32_e32 v132, 16, v57
	v_lshlrev_b32_e32 v142, 16, v53
	s_cselect_b32 s10, 0x4400, 0
	v_lshlrev_b32_e32 v171, 16, v61
	s_add_i32 s13, s10, 0
	v_lshlrev_b32_e32 v1, 1, v152
	v_lshlrev_b32_e32 v187, 16, v65
	s_add_i32 s13, s13, 0x11000
	v_add3_u32 v1, s13, v1, v196
	v_and_b32_e32 v147, 0xffff0000, v55
	v_and_b32_e32 v176, 0xffff0000, v63
	v_lshlrev_b32_e32 v146, 16, v55
	v_lshlrev_b32_e32 v175, 16, v63
	v_add_u32_e32 v206, s33, v150
	s_mov_b32 s10, 0x5040100
	s_cmpk_eq_i32 s33, 0xe00
	s_waitcnt lgkmcnt(0)
	v_fma_f32 v124, v96, v126, v88
	s_nop 0
	v_fma_f32 v125, v92, v134, v84
	v_fma_f32 v126, v97, v127, v89
	v_fma_f32 v127, v93, v135, v85
	v_fma_f32 v135, v95, v139, v87
	s_nop 0
	v_fmac_f32_e32 v124, v100, v140
	s_nop 0
	v_fmac_f32_e32 v125, v104, v144
	v_fmac_f32_e32 v126, v101, v141
	s_nop 0
	v_fmac_f32_e32 v124, v108, v155
	s_nop 0
	v_fmac_f32_e32 v125, v112, v173
	v_lshlrev_b32_e32 v139, 16, v66
	s_nop 0
	v_fmac_f32_e32 v124, v120, v177
	v_fmac_f32_e32 v127, v105, v145
	v_fmac_f32_e32 v126, v109, v170
	s_nop 0
	v_fmac_f32_e32 v125, v116, v139
	v_mul_f32_e32 v139, 0xbfb8aa3b, v124
	v_fmac_f32_e32 v127, v113, v174
	v_and_b32_e32 v140, 0xffff0000, v66
	v_fmac_f32_e32 v126, v121, v186
	v_exp_f32_e32 v139, v139
	v_fmac_f32_e32 v127, v117, v140
	v_mul_f32_e32 v140, 0xbfb8aa3b, v126
	v_exp_f32_e32 v140, v140
	v_fma_f32 v133, v99, v133, v91
	v_fmac_f32_e32 v133, v103, v143
	v_add_f32_e32 v139, 1.0, v139
	v_fma_f32 v134, v94, v138, v86
	v_fmac_f32_e32 v133, v111, v172
	v_and_b32_e32 v138, 0xffff0000, v65
	v_rcp_f32_e32 v139, v139
	v_fmac_f32_e32 v133, v123, v138
	v_add_f32_e32 v138, 1.0, v140
	v_fma_f32 v132, v98, v132, v90
	v_rcp_f32_e32 v138, v138
	v_fmac_f32_e32 v132, v102, v142
	v_fmac_f32_e32 v132, v110, v171
	v_mul_f32_e32 v124, v124, v139
	v_fmac_f32_e32 v132, v122, v187
	v_cvt_pk_bf16_f32 v124, v124, s0
	ds_write_b16 v1, v124
	v_mul_f32_e32 v124, v126, v138
	v_mul_f32_e32 v126, 0xbfb8aa3b, v132
	v_exp_f32_e32 v126, v126
	v_mul_f32_e32 v138, 0xbfb8aa3b, v133
	v_exp_f32_e32 v138, v138
	v_cvt_pk_bf16_f32 v124, v124, s0
	v_add_f32_e32 v126, 1.0, v126
	v_rcp_f32_e32 v126, v126
	ds_write_b16 v1, v124 offset:272
	v_add_f32_e32 v124, 1.0, v138
	v_rcp_f32_e32 v124, v124
	v_mul_f32_e32 v126, v132, v126
	v_cvt_pk_bf16_f32 v126, v126, s0
	ds_write_b16 v1, v126 offset:544
	v_mul_f32_e32 v126, 0xbfb8aa3b, v125
	v_exp_f32_e32 v126, v126
	v_mul_f32_e32 v132, 0xbfb8aa3b, v127
	v_exp_f32_e32 v132, v132
	v_mul_f32_e32 v124, v133, v124
	v_add_f32_e32 v126, 1.0, v126
	v_rcp_f32_e32 v126, v126
	v_fmac_f32_e32 v135, v107, v147
	v_cvt_pk_bf16_f32 v124, v124, s0
	v_fmac_f32_e32 v135, v115, v176
	v_and_b32_e32 v142, 0xffff0000, v67
	ds_write_b16 v1, v124 offset:816
	v_add_f32_e32 v124, 1.0, v132
	v_fmac_f32_e32 v134, v106, v146
	v_fmac_f32_e32 v135, v119, v142
	v_rcp_f32_e32 v124, v124
	v_fmac_f32_e32 v134, v114, v175
	v_lshlrev_b32_e32 v141, 16, v67
	v_mul_f32_e32 v125, v125, v126
	v_mul_f32_e32 v126, 0xbfb8aa3b, v135
	v_fmac_f32_e32 v134, v118, v141
	v_cvt_pk_bf16_f32 v125, v125, s0
	v_exp_f32_e32 v126, v126
	ds_write_b16 v1, v125 offset:1088
	v_mul_f32_e32 v125, 0xbfb8aa3b, v134
	v_mul_f32_e32 v124, v127, v124
	v_exp_f32_e32 v125, v125
	v_cvt_pk_bf16_f32 v124, v124, s0
	ds_write_b16 v1, v124 offset:1360
	v_add_f32_e32 v124, 1.0, v126
	v_rcp_f32_e32 v124, v124
	v_add_f32_e32 v125, 1.0, v125
	v_rcp_f32_e32 v125, v125
	v_lshlrev_b32_e32 v132, 16, v70
	v_mul_f32_e32 v124, v135, v124
	v_cvt_pk_bf16_f32 v124, v124, s0
	v_mul_f32_e32 v125, v134, v125
	ds_write_b16 v1, v124 offset:1904
	v_lshlrev_b32_e32 v124, 16, v68
	v_cvt_pk_bf16_f32 v125, v125, s0
	v_fma_f32 v88, v96, v124, v88
	v_fma_f32 v84, v92, v132, v84
	v_lshlrev_b32_e32 v92, 16, v72
	ds_write_b16 v1, v125 offset:1632
	v_and_b32_e32 v125, 0xffff0000, v68
	v_and_b32_e32 v133, 0xffff0000, v70
	v_fmac_f32_e32 v88, v100, v92
	v_lshlrev_b32_e32 v92, 16, v76
	v_fma_f32 v89, v97, v125, v89
	v_fma_f32 v85, v93, v133, v85
	v_and_b32_e32 v93, 0xffff0000, v72
	v_fmac_f32_e32 v88, v108, v92
	v_lshlrev_b32_e32 v92, 16, v80
	v_fmac_f32_e32 v89, v101, v93
	v_and_b32_e32 v93, 0xffff0000, v76
	v_fmac_f32_e32 v88, v120, v92
	v_fmac_f32_e32 v89, v109, v93
	v_and_b32_e32 v93, 0xffff0000, v80
	v_mul_f32_e32 v92, 0xbfb8aa3b, v88
	v_fmac_f32_e32 v89, v121, v93
	v_exp_f32_e32 v92, v92
	v_mul_f32_e32 v93, 0xbfb8aa3b, v89
	v_exp_f32_e32 v93, v93
	v_lshlrev_b32_e32 v126, 16, v69
	v_add_f32_e32 v92, 1.0, v92
	v_rcp_f32_e32 v92, v92
	v_lshlrev_b32_e32 v134, 16, v71
	v_add_f32_e32 v93, 1.0, v93
	v_fma_f32 v90, v98, v126, v90
	v_fma_f32 v86, v94, v134, v86
	v_lshlrev_b32_e32 v94, 16, v73
	v_rcp_f32_e32 v93, v93
	v_fmac_f32_e32 v90, v102, v94
	v_lshlrev_b32_e32 v94, 16, v77
	v_fmac_f32_e32 v90, v110, v94
	v_lshlrev_b32_e32 v94, 16, v81
	v_mul_f32_e32 v88, v88, v92
	v_fmac_f32_e32 v90, v122, v94
	v_cvt_pk_bf16_f32 v88, v88, s0
	ds_write_b16 v1, v88 offset:128
	v_mul_f32_e32 v88, v89, v93
	v_mul_f32_e32 v89, 0xbfb8aa3b, v90
	v_exp_f32_e32 v89, v89
	v_and_b32_e32 v127, 0xffff0000, v69
	v_and_b32_e32 v135, 0xffff0000, v71
	v_fmac_f32_e32 v91, v99, v127
	v_fmac_f32_e32 v87, v95, v135
	v_and_b32_e32 v95, 0xffff0000, v73
	v_fmac_f32_e32 v91, v103, v95
	v_and_b32_e32 v95, 0xffff0000, v77
	v_fmac_f32_e32 v91, v111, v95
	v_and_b32_e32 v95, 0xffff0000, v81
	v_add_f32_e32 v89, 1.0, v89
	v_fmac_f32_e32 v91, v123, v95
	v_rcp_f32_e32 v89, v89
	v_mul_f32_e32 v92, 0xbfb8aa3b, v91
	v_lshlrev_b32_e32 v96, 16, v74
	v_exp_f32_e32 v92, v92
	v_fmac_f32_e32 v84, v104, v96
	v_lshlrev_b32_e32 v96, 16, v78
	v_and_b32_e32 v97, 0xffff0000, v74
	v_fmac_f32_e32 v84, v112, v96
	v_lshlrev_b32_e32 v96, 16, v82
	v_mul_f32_e32 v89, v90, v89
	v_fmac_f32_e32 v85, v105, v97
	v_and_b32_e32 v97, 0xffff0000, v78
	v_fmac_f32_e32 v84, v116, v96
	v_cvt_pk_bf16_f32 v88, v88, s0
	v_cvt_pk_bf16_f32 v89, v89, s0
	v_fmac_f32_e32 v85, v113, v97
	v_and_b32_e32 v97, 0xffff0000, v82
	ds_write_b16 v1, v88 offset:400
	v_add_f32_e32 v88, 1.0, v92
	ds_write_b16 v1, v89 offset:672
	v_mul_f32_e32 v89, 0xbfb8aa3b, v84
	v_fmac_f32_e32 v85, v117, v97
	v_rcp_f32_e32 v88, v88
	v_exp_f32_e32 v89, v89
	v_mul_f32_e32 v90, 0xbfb8aa3b, v85
	v_exp_f32_e32 v90, v90
	v_mul_f32_e32 v88, v91, v88
	v_add_f32_e32 v89, 1.0, v89
	v_cvt_pk_bf16_f32 v88, v88, s0
	v_rcp_f32_e32 v89, v89
	ds_write_b16 v1, v88 offset:944
	v_add_f32_e32 v88, 1.0, v90
	v_lshlrev_b32_e32 v98, 16, v75
	v_and_b32_e32 v99, 0xffff0000, v75
	v_rcp_f32_e32 v88, v88
	v_fmac_f32_e32 v86, v106, v98
	v_fmac_f32_e32 v87, v107, v99
	v_lshlrev_b32_e32 v98, 16, v79
	v_and_b32_e32 v99, 0xffff0000, v79
	v_fmac_f32_e32 v86, v114, v98
	v_fmac_f32_e32 v87, v115, v99
	v_lshlrev_b32_e32 v98, 16, v83
	v_and_b32_e32 v99, 0xffff0000, v83
	v_mul_f32_e32 v84, v84, v89
	v_fmac_f32_e32 v86, v118, v98
	v_fmac_f32_e32 v87, v119, v99
	v_cvt_pk_bf16_f32 v84, v84, s0
	ds_write_b16 v1, v84 offset:1216
	v_mul_f32_e32 v84, v85, v88
	v_mul_f32_e32 v85, 0xbfb8aa3b, v86
	v_mul_f32_e32 v88, 0xbfb8aa3b, v87
	v_exp_f32_e32 v85, v85
	v_exp_f32_e32 v88, v88
	v_cvt_pk_bf16_f32 v84, v84, s0
	ds_write_b16 v1, v84 offset:1488
	v_add_f32_e32 v85, 1.0, v85
	v_add_f32_e32 v84, 1.0, v88
	v_rcp_f32_e32 v85, v85
	v_rcp_f32_e32 v84, v84
	v_lshl_add_u64 v[176:177], s[2:3], 0, v[166:167]
	v_mul_f32_e32 v85, v86, v85
	v_mul_f32_e32 v84, v87, v84
	v_cvt_pk_bf16_f32 v85, v85, s0
	v_cvt_pk_bf16_f32 v84, v84, s0
	ds_write_b16 v1, v85 offset:1760
	ds_write_b16 v1, v84 offset:2032
	v_add_u32_e32 v1, s33, v200
	v_add_u32_e32 v84, 0x23000, v206
	ds_read_b32 v155, v1
	ds_read_b128 v[84:87], v84
	v_add_u32_e32 v1, 0x22000, v206
	ds_read_b128 v[88:91], v1
	global_load_dwordx4 v[92:95], v[130:131], off offset:-4096
	global_load_dwordx4 v[100:103], v[130:131], off
	s_waitcnt lgkmcnt(1)
	v_sub_f32_e32 v1, v155, v84
	v_mul_f32_e32 v1, 0x3fb8aa3b, v1
	v_exp_f32_e32 v1, v1
	v_sub_f32_e32 v84, v155, v85
	v_mul_f32_e32 v84, 0x3fb8aa3b, v84
	v_sub_f32_e32 v85, v155, v87
	v_mul_f32_e32 v1, v20, v1
	s_waitcnt lgkmcnt(0)
	v_mul_f32_e32 v1, v88, v1
	v_exp_f32_e32 v88, v84
	v_sub_f32_e32 v84, v155, v86
	v_mul_f32_e32 v84, 0x3fb8aa3b, v84
	v_mul_f32_e32 v85, 0x3fb8aa3b, v85
	v_exp_f32_e32 v84, v84
	v_exp_f32_e32 v85, v85
	v_mul_f32_e32 v86, v21, v88
	v_mul_f32_e32 v86, v89, v86
	v_cndmask_b32_e64 v1, v1, 0, s[20:21]
	v_pk_mul_f32 v[84:85], v[22:23], v[84:85]
	v_cndmask_b32_e64 v86, 0, v86, s[22:23]
	v_pk_mul_f32 v[84:85], v[90:91], v[84:85]
	v_cvt_pk_bf16_f32 v86, v1, v86
	v_cvt_pk_bf16_f32 v1, v84, v85
	v_cndmask_b32_e64 v84, v1, 0, s[26:27]
	v_lshrrev_b32_e32 v1, 16, v1
	v_cndmask_b32_e64 v1, v1, 0, s[24:25]
	v_perm_b32 v87, v1, v84, s10
	ds_write_b64 v195, v[86:87]
	v_add_u32_e32 v1, 0x23040, v206
	ds_read_b128 v[84:87], v1
	v_add_u32_e32 v1, 0x22040, v206
	ds_read_b128 v[88:91], v1
	s_waitcnt lgkmcnt(1)
	v_sub_f32_e32 v1, v155, v84
	v_mul_f32_e32 v1, 0x3fb8aa3b, v1
	v_exp_f32_e32 v84, v1
	v_sub_f32_e32 v1, v155, v85
	v_mul_f32_e32 v1, 0x3fb8aa3b, v1
	v_exp_f32_e32 v85, v1
	v_sub_f32_e32 v1, v155, v86
	v_mul_f32_e32 v1, 0x3fb8aa3b, v1
	v_exp_f32_e32 v86, v1
	v_sub_f32_e32 v1, v155, v87
	v_mul_f32_e32 v1, 0x3fb8aa3b, v1
	v_exp_f32_e32 v87, v1
	v_pk_mul_f32 v[84:85], v[24:25], v[84:85]
	v_pk_mul_f32 v[86:87], v[26:27], v[86:87]
	s_waitcnt lgkmcnt(0)
	v_pk_mul_f32 v[84:85], v[88:89], v[84:85]
	v_pk_mul_f32 v[86:87], v[90:91], v[86:87]
	v_cvt_pk_bf16_f32 v1, v84, v85
	v_cndmask_b32_e64 v84, v1, 0, s[30:31]
	v_lshrrev_b32_e32 v1, 16, v1
	v_cndmask_b32_e64 v1, v1, 0, s[28:29]
	v_perm_b32 v84, v1, v84, s10
	v_cvt_pk_bf16_f32 v1, v86, v87
	v_cndmask_b32_e64 v85, v1, 0, s[36:37]
	v_lshrrev_b32_e32 v1, 16, v1
	v_cndmask_b32_e64 v1, v1, 0, s[34:35]
	v_perm_b32 v85, v1, v85, s10
	ds_write_b64 v195, v[84:85] offset:32
	v_add_u32_e32 v1, 0x23080, v206
	ds_read_b128 v[88:91], v1
	v_add_u32_e32 v1, 0x22080, v206
	global_load_dwordx4 v[112:115], v[136:137], off
	global_load_dwordx4 v[84:87], v[136:137], off offset:64
	ds_read_b128 v[96:99], v1
	s_waitcnt lgkmcnt(1)
	v_sub_f32_e32 v1, v155, v88
	v_mul_f32_e32 v1, 0x3fb8aa3b, v1
	v_exp_f32_e32 v104, v1
	v_sub_f32_e32 v1, v155, v89
	v_mul_f32_e32 v1, 0x3fb8aa3b, v1
	v_exp_f32_e32 v105, v1
	v_sub_f32_e32 v1, v155, v90
	v_mul_f32_e32 v1, 0x3fb8aa3b, v1
	v_exp_f32_e32 v106, v1
	v_sub_f32_e32 v1, v155, v91
	v_mul_f32_e32 v1, 0x3fb8aa3b, v1
	v_exp_f32_e32 v107, v1
	v_pk_mul_f32 v[104:105], v[28:29], v[104:105]
	global_load_dwordx4 v[108:111], v[2:3], off offset:64
	global_load_dwordx4 v[88:91], v[2:3], off offset:128
	s_waitcnt lgkmcnt(0)
	v_pk_mul_f32 v[96:97], v[96:97], v[104:105]
	v_pk_mul_f32 v[104:105], v[30:31], v[106:107]
	v_cvt_pk_bf16_f32 v1, v96, v97
	v_cndmask_b32_e64 v96, v1, 0, s[40:41]
	v_lshrrev_b32_e32 v1, 16, v1
	v_pk_mul_f32 v[98:99], v[98:99], v[104:105]
	v_cndmask_b32_e64 v1, v1, 0, s[38:39]
	v_perm_b32 v96, v1, v96, s10
	v_cvt_pk_bf16_f32 v1, v98, v99
	v_cndmask_b32_e64 v97, v1, 0, s[44:45]
	v_lshrrev_b32_e32 v1, 16, v1
	v_cndmask_b32_e64 v1, v1, 0, s[42:43]
	v_perm_b32 v97, v1, v97, s10
	ds_write_b64 v195, v[96:97] offset:64
	v_add_u32_e32 v1, 0x230c0, v206
	ds_read_b128 v[104:107], v1
	v_add_u32_e32 v1, 0x220c0, v206
	global_load_dwordx4 v[116:119], v[130:131], off offset:64
	global_load_dwordx4 v[96:99], v[130:131], off offset:128
	ds_read_b128 v[120:123], v1
	s_waitcnt lgkmcnt(1)
	v_sub_f32_e32 v1, v155, v104
	v_mul_f32_e32 v1, 0x3fb8aa3b, v1
	v_exp_f32_e32 v132, v1
	v_sub_f32_e32 v1, v155, v105
	v_mul_f32_e32 v1, 0x3fb8aa3b, v1
	v_exp_f32_e32 v133, v1
	v_sub_f32_e32 v1, v155, v106
	v_mul_f32_e32 v1, 0x3fb8aa3b, v1
	v_exp_f32_e32 v134, v1
	v_sub_f32_e32 v1, v155, v107
	v_mul_f32_e32 v1, 0x3fb8aa3b, v1
	v_exp_f32_e32 v135, v1
	global_load_dwordx4 v[124:127], v[128:129], off offset:64
	global_load_dwordx4 v[104:107], v[2:3], off offset:192
	v_pk_mul_f32 v[2:3], v[32:33], v[132:133]
	s_waitcnt lgkmcnt(0)
	v_pk_mul_f32 v[2:3], v[120:121], v[2:3]
	v_pk_mul_f32 v[120:121], v[34:35], v[134:135]
	v_cvt_pk_bf16_f32 v1, v2, v3
	v_cndmask_b32_e64 v2, v1, 0, s[48:49]
	v_lshrrev_b32_e32 v1, 16, v1
	v_pk_mul_f32 v[120:121], v[122:123], v[120:121]
	v_cndmask_b32_e64 v1, v1, 0, s[46:47]
	v_perm_b32 v2, v1, v2, s10
	v_cvt_pk_bf16_f32 v1, v120, v121
	v_cndmask_b32_e64 v3, v1, 0, s[52:53]
	v_lshrrev_b32_e32 v1, 16, v1
	v_cndmask_b32_e64 v1, v1, 0, s[50:51]
	v_perm_b32 v3, v1, v3, s10
	ds_write_b64 v195, v[2:3] offset:96
	v_add_u32_e32 v1, 0x23100, v206
	ds_read_b128 v[132:135], v1
	v_add_u32_e32 v1, 0x22100, v206
	global_load_dwordx4 v[144:147], v[136:137], off offset:-4096
	global_load_dwordx4 v[120:123], v[130:131], off offset:192
	ds_read_b128 v[138:141], v1
	s_waitcnt lgkmcnt(1)
	v_sub_f32_e32 v1, v155, v132
	v_mul_f32_e32 v1, 0x3fb8aa3b, v1
	v_exp_f32_e32 v2, v1
	v_sub_f32_e32 v1, v155, v133
	v_mul_f32_e32 v1, 0x3fb8aa3b, v1
	v_exp_f32_e32 v3, v1
	v_sub_f32_e32 v1, v155, v134
	v_mul_f32_e32 v1, 0x3fb8aa3b, v1
	v_exp_f32_e32 v142, v1
	v_sub_f32_e32 v1, v155, v135
	v_mul_f32_e32 v1, 0x3fb8aa3b, v1
	v_exp_f32_e32 v143, v1
	v_pk_mul_f32 v[2:3], v[36:37], v[2:3]
	global_load_dwordx4 v[132:135], v[128:129], off offset:128
	s_nop 0
	global_load_dwordx4 v[128:131], v[128:129], off offset:192
	s_waitcnt lgkmcnt(0)
	v_pk_mul_f32 v[2:3], v[138:139], v[2:3]
	v_pk_mul_f32 v[138:139], v[38:39], v[142:143]
	v_cvt_pk_bf16_f32 v1, v2, v3
	v_cndmask_b32_e64 v2, v1, 0, s[56:57]
	v_lshrrev_b32_e32 v1, 16, v1
	v_pk_mul_f32 v[138:139], v[140:141], v[138:139]
	v_cndmask_b32_e64 v1, v1, 0, s[54:55]
	v_perm_b32 v2, v1, v2, s10
	v_cvt_pk_bf16_f32 v1, v138, v139
	v_cndmask_b32_e64 v3, v1, 0, s[60:61]
	v_lshrrev_b32_e32 v1, 16, v1
	v_cndmask_b32_e64 v1, v1, 0, s[58:59]
	v_perm_b32 v3, v1, v3, s10
	ds_write_b64 v195, v[2:3] offset:128
	v_add_u32_e32 v1, 0x23140, v206
	ds_read_b128 v[170:173], v1
	v_add_u32_e32 v1, 0x22140, v206
	global_load_dwordx4 v[140:143], v[136:137], off offset:128
	s_nop 0
	global_load_dwordx4 v[136:139], v[136:137], off offset:192
	ds_read_b128 v[186:189], v1
	s_waitcnt lgkmcnt(1)
	v_sub_f32_e32 v1, v155, v170
	v_mul_f32_e32 v1, 0x3fb8aa3b, v1
	v_exp_f32_e32 v2, v1
	v_sub_f32_e32 v1, v155, v171
	v_mul_f32_e32 v1, 0x3fb8aa3b, v1
	v_exp_f32_e32 v3, v1
	v_sub_f32_e32 v1, v155, v172
	v_mul_f32_e32 v1, 0x3fb8aa3b, v1
	v_exp_f32_e32 v192, v1
	v_sub_f32_e32 v1, v155, v173
	global_load_dwordx2 v[190:191], v[176:177], off offset:-64
	global_load_dwordx2 v[174:175], v[176:177], off offset:-32
	global_load_dwordx2 v[172:173], v[176:177], off
	global_load_dwordx2 v[170:171], v[176:177], off offset:32
	v_mul_f32_e32 v1, 0x3fb8aa3b, v1
	v_exp_f32_e32 v193, v1
	v_pk_mul_f32 v[2:3], v[40:41], v[2:3]
	s_waitcnt lgkmcnt(0)
	v_pk_mul_f32 v[2:3], v[186:187], v[2:3]
	v_pk_mul_f32 v[186:187], v[42:43], v[192:193]
	v_cvt_pk_bf16_f32 v1, v2, v3
	v_cndmask_b32_e64 v2, v1, 0, s[64:65]
	v_lshrrev_b32_e32 v1, 16, v1
	v_pk_mul_f32 v[186:187], v[188:189], v[186:187]
	v_cndmask_b32_e64 v1, v1, 0, s[62:63]
	v_perm_b32 v2, v1, v2, s10
	v_cvt_pk_bf16_f32 v1, v186, v187
	v_cndmask_b32_e64 v3, v1, 0, s[68:69]
	v_lshrrev_b32_e32 v1, 16, v1
	v_cndmask_b32_e64 v1, v1, 0, s[66:67]
	v_perm_b32 v3, v1, v3, s10
	ds_write_b64 v195, v[2:3] offset:160
	v_add_u32_e32 v1, 0x23180, v206
	ds_read_b128 v[186:189], v1
	v_add_u32_e32 v1, 0x22180, v206
	ds_read_b128 v[202:205], v1
	s_waitcnt lgkmcnt(1)
	v_sub_f32_e32 v1, v155, v186
	v_mul_f32_e32 v1, 0x3fb8aa3b, v1
	v_exp_f32_e32 v2, v1
	v_sub_f32_e32 v1, v155, v187
	v_mul_f32_e32 v1, 0x3fb8aa3b, v1
	v_exp_f32_e32 v3, v1
	v_sub_f32_e32 v1, v155, v188
	v_mul_f32_e32 v1, 0x3fb8aa3b, v1
	v_exp_f32_e32 v186, v1
	v_sub_f32_e32 v1, v155, v189
	v_mul_f32_e32 v1, 0x3fb8aa3b, v1
	v_exp_f32_e32 v187, v1
	v_pk_mul_f32 v[2:3], v[44:45], v[2:3]
	v_pk_mul_f32 v[186:187], v[46:47], v[186:187]
	s_waitcnt lgkmcnt(0)
	v_pk_mul_f32 v[2:3], v[202:203], v[2:3]
	v_pk_mul_f32 v[186:187], v[204:205], v[186:187]
	v_cvt_pk_bf16_f32 v1, v2, v3
	v_cndmask_b32_e64 v2, v1, 0, s[72:73]
	v_lshrrev_b32_e32 v1, 16, v1
	v_cndmask_b32_e64 v1, v1, 0, s[70:71]
	v_perm_b32 v2, v1, v2, s10
	v_cvt_pk_bf16_f32 v1, v186, v187
	v_cndmask_b32_e64 v3, v1, 0, s[76:77]
	v_lshrrev_b32_e32 v1, 16, v1
	v_cndmask_b32_e64 v1, v1, 0, s[74:75]
	v_perm_b32 v3, v1, v3, s10
	ds_write_b64 v195, v[2:3] offset:192
	v_add_u32_e32 v1, 0x231c0, v206
	ds_read_b128 v[186:189], v1
	v_add_u32_e32 v1, 0x221c0, v206
	ds_read_b128 v[202:205], v1
	s_waitcnt lgkmcnt(1)
	v_sub_f32_e32 v1, v155, v186
	v_mul_f32_e32 v1, 0x3fb8aa3b, v1
	v_exp_f32_e32 v2, v1
	v_sub_f32_e32 v1, v155, v187
	v_mul_f32_e32 v1, 0x3fb8aa3b, v1
	v_exp_f32_e32 v3, v1
	v_sub_f32_e32 v1, v155, v188
	v_mul_f32_e32 v1, 0x3fb8aa3b, v1
	v_exp_f32_e32 v186, v1
	v_sub_f32_e32 v1, v155, v189
	v_mul_f32_e32 v1, 0x3fb8aa3b, v1
	v_exp_f32_e32 v187, v1
	v_pk_mul_f32 v[2:3], v[48:49], v[2:3]
	v_pk_mul_f32 v[186:187], v[50:51], v[186:187]
	s_waitcnt lgkmcnt(0)
	v_pk_mul_f32 v[2:3], v[202:203], v[2:3]
	v_pk_mul_f32 v[186:187], v[204:205], v[186:187]
	v_cvt_pk_bf16_f32 v1, v2, v3
	v_cndmask_b32_e64 v2, v1, 0, s[80:81]
	v_lshrrev_b32_e32 v1, 16, v1
	v_cndmask_b32_e64 v1, v1, 0, s[78:79]
	v_perm_b32 v2, v1, v2, s10
	v_cvt_pk_bf16_f32 v1, v186, v187
	v_cndmask_b32_e64 v3, v1, 0, s[84:85]
	v_lshrrev_b32_e32 v1, 16, v1
	v_cndmask_b32_e64 v1, v1, 0, s[82:83]
	v_perm_b32 v3, v1, v3, s10
	ds_write_b64 v195, v[2:3] offset:224
	s_waitcnt lgkmcnt(0)
	s_barrier
	s_cbranch_scc1 .LBB0_1125
	v_mov_b32_e32 v54, v0
	v_mov_b32_e32 v55, v0
	v_mov_b32_e32 v52, v0
	v_mov_b32_e32 v53, v0
	v_mov_b64_e32 v[58:59], v[54:55]
	v_lshl_add_u64 v[192:193], s[2:3], 0, v[168:169]
	v_mov_b64_e32 v[56:57], v[52:53]
	s_mov_b64 s[10:11], exec
	v_readlane_b32 vcc_lo, v255, 42
	v_readlane_b32 vcc_hi, v255, 43
	s_and_b64 vcc, s[10:11], vcc
	s_mov_b64 exec, vcc
	s_cbranch_execz .LBB0_1129
	v_add_co_u32_e32 v2, vcc, 0x31fa000, v192
	s_nop 1
	v_addc_co_u32_e32 v3, vcc, 0, v193, vcc
	global_load_dwordx4 v[56:59], v[2:3], off offset:3200
